# k22: k21 + S2 second conv task: its 8 own-row and 3 halo-row loads issued early with the first task's decay loads (regs v196-v239), original loads become moves
# speedup vs baseline: 1.0088x; 1.0088x over previous
.LBB0_1377:
	s_or_b64 exec, exec, s[2:3]
	s_or_b32 s2, s0, 0x7f
	s_ashr_i32 s3, s2, 31
	s_lshl_b32 s39, s63, 2
	s_lshl_b64 s[2:3], s[2:3], 7
	s_add_u32 s40, s18, s2
	s_addc_u32 s41, s19, s3
	s_ashr_i32 s2, s0, 6
	v_add_u32_e32 v22, s0, v150
	v_mov_b32_e32 v5, v121
	v_or_b32_e32 v18, s39, v151
	s_ashr_i32 s3, s2, 31
	v_ashrrev_i32_e32 v23, 31, v22
	v_lshl_add_u64 v[128:129], v[2:3], 0, v[4:5]
	v_lshlrev_b32_e32 v25, 2, v18
	s_lshl_b64 s[2:3], s[2:3], 7
	v_lshlrev_b64 v[26:27], 7, v[22:23]
	v_add_co_u32_e32 v2, vcc, 0x2000, v128
	s_add_u32 s42, s48, s2
	v_or_b32_e32 v26, v26, v25
	v_addc_co_u32_e32 v3, vcc, 0, v129, vcc
	s_addc_u32 s43, s49, s3
	v_lshl_add_u64 v[28:29], s[18:19], 0, v[26:27]
	global_load_dwordx4 v[74:77], v[2:3], off
	global_load_dword v18, v25, s[40:41]
	global_load_dword v21, v[28:29], off
	global_load_dword v20, v25, s[42:43]
	v_lshl_add_u64 v[26:27], s[16:17], 0, v[26:27]
	v_add_co_u32_e32 v2, vcc, s58, v128
	global_load_dwordx4 v[82:85], v[128:129], off
	s_nop 0
	v_addc_co_u32_e32 v3, vcc, 0, v129, vcc
	global_load_dwordx4 v[58:61], v[2:3], off
	s_mov_b32 s1, 0xa000
	v_readlane_b32 s80, v254, 34
	v_readlane_b32 s92, v254, 46
	v_readlane_b32 s93, v254, 47
	v_lshlrev_b32_e32 v120, 2, v24
	v_readlane_b32 s94, v254, 48
	v_readlane_b32 s95, v254, 49
	s_mov_b64 s[68:69], s[92:93]
	s_mov_b64 s[70:71], s[94:95]
	s_waitcnt vmcnt(6)
	v_lshlrev_b32_e32 v86, 16, v66
	v_and_b32_e32 v87, 0xffff0000, v66
	v_lshlrev_b32_e32 v66, 16, v67
	v_and_b32_e32 v67, 0xffff0000, v67
	v_lshlrev_b32_e32 v94, 16, v71
	v_and_b32_e32 v95, 0xffff0000, v71
	v_lshlrev_b32_e32 v92, 16, v70
	v_and_b32_e32 v93, 0xffff0000, v70
	v_lshlrev_b32_e32 v100, 16, v79
	v_and_b32_e32 v101, 0xffff0000, v79
	v_lshlrev_b32_e32 v98, 16, v78
	v_and_b32_e32 v99, 0xffff0000, v78
	v_lshlrev_b32_e32 v108, 16, v73
	v_and_b32_e32 v109, 0xffff0000, v73
	v_lshlrev_b32_e32 v102, 16, v80
	v_and_b32_e32 v103, 0xffff0000, v80
	v_lshlrev_b32_e32 v106, 16, v81
	v_and_b32_e32 v107, 0xffff0000, v81
	v_lshl_or_b32 v136, s63, 7, v149
	v_readlane_b32 s81, v254, 35
	v_readlane_b32 s82, v254, 36
	v_readlane_b32 s83, v254, 37
	v_readlane_b32 s84, v254, 38
	v_readlane_b32 s85, v254, 39
	v_readlane_b32 s86, v254, 40
	v_readlane_b32 s87, v254, 41
	v_readlane_b32 s88, v254, 42
	v_readlane_b32 s89, v254, 43
	v_readlane_b32 s90, v254, 44
	v_readlane_b32 s91, v254, 45
	s_waitcnt vmcnt(5)
	v_lshlrev_b32_e32 v104, 16, v75
	v_and_b32_e32 v105, 0xffff0000, v75
	v_lshlrev_b32_e32 v132, 16, v77
	global_load_dword v164, v[26:27], off
	global_load_dword v165, v[28:29], off offset:128
	global_load_dword v166, v[26:27], off offset:128
	global_load_dword v167, v[28:29], off offset:256
	global_load_dword v168, v[26:27], off offset:256
	global_load_dword v169, v[28:29], off offset:384
	global_load_dword v170, v[26:27], off offset:384
	global_load_dword v171, v[28:29], off offset:512
	global_load_dword v172, v[26:27], off offset:512
	global_load_dword v173, v[28:29], off offset:640
	global_load_dword v174, v[26:27], off offset:640
	global_load_dword v175, v[28:29], off offset:768
	global_load_dword v176, v[26:27], off offset:768
	global_load_dword v177, v[28:29], off offset:896
	global_load_dword v178, v[26:27], off offset:896
	v_or_b32_e32 v190, s65, v152
	v_lshlrev_b32_e32 v190, 13, v190
	v_mov_b32_e32 v191, 0
	v_lshlrev_b32_e32 v192, 1, v136
	v_mov_b32_e32 v193, 0
	v_lshl_add_u64 v[192:193], s[46:47], 0, v[192:193]
	v_lshl_add_u64 v[192:193], v[192:193], 0, v[190:191]
	global_load_dwordx4 v[196:199], v[192:193], off
	v_mov_b32_e32 v190, v192
	v_mov_b32_e32 v191, v193
	v_add_co_u32_e32 v192, vcc, 0x2000, v192
	s_nop 1
	v_addc_co_u32_e32 v193, vcc, 0, v193, vcc
	global_load_dwordx4 v[200:203], v[192:193], off
	v_add_co_u32_e32 v192, vcc, 0x2000, v192
	s_nop 1
	v_addc_co_u32_e32 v193, vcc, 0, v193, vcc
	global_load_dwordx4 v[204:207], v[192:193], off
	v_add_co_u32_e32 v192, vcc, 0x2000, v192
	s_nop 1
	v_addc_co_u32_e32 v193, vcc, 0, v193, vcc
	global_load_dwordx4 v[208:211], v[192:193], off
	v_add_co_u32_e32 v192, vcc, 0x2000, v192
	s_nop 1
	v_addc_co_u32_e32 v193, vcc, 0, v193, vcc
	global_load_dwordx4 v[212:215], v[192:193], off
	v_add_co_u32_e32 v192, vcc, 0x2000, v192
	s_nop 1
	v_addc_co_u32_e32 v193, vcc, 0, v193, vcc
	global_load_dwordx4 v[216:219], v[192:193], off
	v_add_co_u32_e32 v192, vcc, 0x2000, v192
	s_nop 1
	v_addc_co_u32_e32 v193, vcc, 0, v193, vcc
	global_load_dwordx4 v[220:223], v[192:193], off
	v_add_co_u32_e32 v192, vcc, 0x2000, v192
	s_nop 1
	v_addc_co_u32_e32 v193, vcc, 0, v193, vcc
	global_load_dwordx4 v[224:227], v[192:193], off
	s_waitcnt vmcnt(25)
	v_cndmask_b32_e64 v19, 0, v20, s[6:7]
	v_pk_add_f32 v[20:21], v[18:19], v[20:21]
	v_and_b32_e32 v133, 0xffff0000, v77
	v_sub_f32_e32 v180, v20, v21
	v_add_co_u32_e32 v194, vcc, 0xffffa000, v190
	s_nop 1
	v_addc_co_u32_e32 v195, vcc, -1, v191, vcc
	v_lshlrev_b32_e32 v240, 1, v136
	v_mov_b32_e32 v241, 0
	v_lshl_add_u64 v[240:241], s[44:45], 0, v[240:241]
	v_cndmask_b32_e64 v194, v240, v194, s[8:9]
	v_cndmask_b32_e64 v195, v241, v195, s[8:9]
	s_orn2_b64 vcc, s[8:9], s[12:13]
	s_and_saveexec_b64 s[100:101], vcc
	global_load_dwordx4 v[228:231], v[194:195], off
	v_add_co_u32_e32 v194, vcc, 0x2000, v194
	s_nop 1
	v_addc_co_u32_e32 v195, vcc, 0, v195, vcc
	global_load_dwordx4 v[232:235], v[194:195], off
	v_add_co_u32_e32 v194, vcc, 0x2000, v194
	s_nop 1
	v_addc_co_u32_e32 v195, vcc, 0, v195, vcc
	global_load_dwordx4 v[236:239], v[194:195], off
	s_mov_b64 exec, s[100:101]
	s_waitcnt vmcnt(0)
	v_add_f32_e32 v181, v19, v165
	v_sub_f32_e32 v181, v20, v181
	v_add_f32_e32 v182, v19, v167
	v_sub_f32_e32 v182, v20, v182
	v_add_f32_e32 v183, v19, v169
	v_sub_f32_e32 v183, v20, v183
	v_add_f32_e32 v184, v19, v171
	v_sub_f32_e32 v184, v20, v184
	v_add_f32_e32 v185, v19, v173
	v_sub_f32_e32 v185, v20, v185
	v_add_f32_e32 v186, v19, v175
	v_sub_f32_e32 v186, v20, v186
	v_add_f32_e32 v187, v19, v177
	v_sub_f32_e32 v187, v20, v187
	v_exp_f32_e32 v180, v180
	v_exp_f32_e32 v181, v181
	v_exp_f32_e32 v182, v182
	v_exp_f32_e32 v183, v183
	v_exp_f32_e32 v184, v184
	v_exp_f32_e32 v185, v185
	v_exp_f32_e32 v186, v186
	v_exp_f32_e32 v187, v187
	v_mul_f32_e32 v137, v164, v180
	v_mul_f32_e32 v138, v166, v181
	v_mul_f32_e32 v139, v168, v182
	v_mul_f32_e32 v140, v170, v183
	v_mul_f32_e32 v141, v172, v184
	v_mul_f32_e32 v142, v174, v185
	v_mul_f32_e32 v143, v176, v186
	v_mov_b32_e32 v20, v187
	v_mov_b32_e32 v18, v178
	v_add_co_u32_e32 v2, vcc, s57, v128
	v_lshl_add_u64 v[22:23], s[68:69], 0, v[120:121]
	s_nop 0
	v_addc_co_u32_e32 v3, vcc, 0, v129, vcc
	global_load_dwordx4 v[38:41], v[2:3], off
	v_add_co_u32_e32 v2, vcc, s59, v128
	v_lshl_add_u64 v[24:25], v[22:23], 0, s[22:23]
	s_nop 0
	v_addc_co_u32_e32 v3, vcc, 0, v129, vcc
	global_load_dwordx4 v[14:17], v[2:3], off
	v_add_co_u32_e32 v2, vcc, s1, v128
	v_lshlrev_b32_e32 v88, 16, v83
	s_nop 0
	v_addc_co_u32_e32 v3, vcc, 0, v129, vcc
	global_load_dwordx4 v[10:13], v[2:3], off
	v_add_co_u32_e32 v2, vcc, s60, v128
	v_and_b32_e32 v89, 0xffff0000, v83
	s_nop 0
	v_addc_co_u32_e32 v3, vcc, 0, v129, vcc
	global_load_dwordx4 v[6:9], v[2:3], off
	v_add_co_u32_e32 v2, vcc, s56, v128
	v_lshlrev_b32_e32 v90, 16, v84
	s_nop 0
	v_addc_co_u32_e32 v3, vcc, 0, v129, vcc
	v_add_co_u32_e32 v26, vcc, s58, v22
	global_load_dwordx4 v[2:5], v[2:3], off
	s_nop 0
	v_addc_co_u32_e32 v27, vcc, 0, v23, vcc
	v_add_co_u32_e32 v30, vcc, s59, v22
	v_and_b32_e32 v91, 0xffff0000, v84
	s_nop 0
	v_addc_co_u32_e32 v31, vcc, 0, v23, vcc
	v_lshlrev_b32_e32 v96, 16, v85
	v_and_b32_e32 v97, 0xffff0000, v85
	v_lshlrev_b32_e32 v130, 16, v61
	v_and_b32_e32 v131, 0xffff0000, v61
	s_waitcnt vmcnt(5)
	v_mul_f32_e32 v144, v18, v20
	global_load_dwordx4 v[18:21], v120, s[68:69] offset:16
	global_load_dwordx4 v[42:45], v120, s[68:69]
	global_load_dwordx4 v[50:53], v[26:27], off
	s_nop 0
	global_load_dwordx4 v[26:29], v[24:25], off offset:16
	v_lshl_add_u64 v[24:25], v[22:23], 0, s[26:27]
	global_load_dwordx4 v[54:57], v[30:31], off
	s_nop 0
	global_load_dwordx4 v[30:33], v[24:25], off offset:16
	v_lshl_add_u64 v[24:25], v[22:23], 0, s[30:31]
	v_add_co_u32_e32 v22, vcc, s60, v22
	s_waitcnt vmcnt(10)
	v_lshlrev_b32_e32 v114, 16, v39
	v_addc_co_u32_e32 v23, vcc, 0, v23, vcc
	global_load_dwordx4 v[46:49], v[22:23], off
	s_nop 0
	global_load_dwordx4 v[22:25], v[24:25], off offset:16
	s_nop 0
	global_load_dwordx4 v[34:37], v120, s[70:71] offset:16
	global_load_dwordx4 v[62:65], v120, s[70:71]
	v_and_b32_e32 v115, 0xffff0000, v39
	v_lshlrev_b32_e32 v110, 16, v38
	v_and_b32_e32 v111, 0xffff0000, v38
	v_lshlrev_b32_e32 v116, 16, v41
	v_and_b32_e32 v117, 0xffff0000, v41
	s_waitcnt vmcnt(13)
	v_lshlrev_b32_e32 v112, 16, v15
	v_and_b32_e32 v113, 0xffff0000, v15
	s_waitcnt vmcnt(12)
	v_lshlrev_b32_e32 v134, 16, v11
	v_and_b32_e32 v135, 0xffff0000, v11
	v_lshlrev_b32_e32 v120, 1, v136
	s_waitcnt vmcnt(0)
	v_pk_fma_f32 v[66:67], v[44:45], v[66:67], v[64:65]
	v_pk_fma_f32 v[86:87], v[42:43], v[86:87], v[62:63]
	v_pk_fma_f32 v[66:67], v[52:53], v[94:95], v[66:67]
	v_pk_fma_f32 v[70:71], v[50:51], v[92:93], v[86:87]
	v_pk_fma_f32 v[66:67], v[56:57], v[100:101], v[66:67]
	v_pk_fma_f32 v[70:71], v[54:55], v[98:99], v[70:71]
	v_lshlrev_b32_e32 v86, 16, v82
	v_and_b32_e32 v87, 0xffff0000, v82
	v_pk_fma_f32 v[66:67], v[48:49], v[88:89], v[66:67]
	v_pk_fma_f32 v[70:71], v[46:47], v[86:87], v[70:71]
	v_pk_mul_f32 v[78:79], v[66:67], s[36:37] op_sel_hi:[1,0]
	v_pk_mul_f32 v[82:83], v[70:71], s[36:37] op_sel_hi:[1,0]
	v_exp_f32_e32 v78, v78
	v_exp_f32_e32 v79, v79
	v_exp_f32_e32 v82, v82
	v_exp_f32_e32 v83, v83
	v_pk_add_f32 v[78:79], v[78:79], 1.0 op_sel_hi:[1,0]
	s_nop 0
	v_rcp_f32_e32 v78, v78
	v_pk_add_f32 v[82:83], v[82:83], 1.0 op_sel_hi:[1,0]
	v_rcp_f32_e32 v79, v79
	v_rcp_f32_e32 v82, v82
	v_rcp_f32_e32 v83, v83
	v_pk_mul_f32 v[66:67], v[66:67], v[78:79]
	v_lshlrev_b32_e32 v78, 16, v68
	v_and_b32_e32 v79, 0xffff0000, v68
	v_lshlrev_b32_e32 v68, 16, v69
	v_and_b32_e32 v69, 0xffff0000, v69
	v_pk_mul_f32 v[70:71], v[70:71], v[82:83]
	v_pk_fma_f32 v[68:69], v[20:21], v[68:69], v[36:37]
	v_pk_fma_f32 v[78:79], v[18:19], v[78:79], v[34:35]
	v_lshlrev_b32_e32 v82, 16, v72
	v_and_b32_e32 v83, 0xffff0000, v72
	v_pk_fma_f32 v[68:69], v[28:29], v[108:109], v[68:69]
	v_pk_fma_f32 v[72:73], v[26:27], v[82:83], v[78:79]
	v_pk_fma_f32 v[68:69], v[32:33], v[106:107], v[68:69]
	v_pk_fma_f32 v[72:73], v[30:31], v[102:103], v[72:73]
	v_pk_fma_f32 v[68:69], v[24:25], v[96:97], v[68:69]
	v_pk_fma_f32 v[72:73], v[22:23], v[90:91], v[72:73]
	v_pk_mul_f32 v[78:79], v[68:69], s[36:37] op_sel_hi:[1,0]
	v_pk_mul_f32 v[80:81], v[72:73], s[36:37] op_sel_hi:[1,0]
	v_exp_f32_e32 v78, v78
	v_exp_f32_e32 v80, v80
	v_exp_f32_e32 v81, v81
	v_exp_f32_e32 v79, v79
	v_pk_fma_f32 v[82:83], v[18:19], v[82:83], v[34:35]
	v_pk_add_f32 v[80:81], v[80:81], 1.0 op_sel_hi:[1,0]
	v_pk_add_f32 v[78:79], v[78:79], 1.0 op_sel_hi:[1,0]
	v_rcp_f32_e32 v80, v80
	v_rcp_f32_e32 v81, v81
	v_rcp_f32_e32 v78, v78
	v_rcp_f32_e32 v79, v79
	v_pk_fma_f32 v[82:83], v[26:27], v[102:103], v[82:83]
	v_pk_mul_f32 v[72:73], v[72:73], v[80:81]
	v_pk_fma_f32 v[80:81], v[42:43], v[92:93], v[62:63]
	v_pk_mul_f32 v[68:69], v[68:69], v[78:79]
	v_pk_fma_f32 v[78:79], v[44:45], v[94:95], v[64:65]
	v_pk_fma_f32 v[80:81], v[50:51], v[98:99], v[80:81]
	v_pk_fma_f32 v[78:79], v[52:53], v[100:101], v[78:79]
	v_pk_fma_f32 v[80:81], v[54:55], v[86:87], v[80:81]
	v_pk_fma_f32 v[78:79], v[56:57], v[88:89], v[78:79]
	v_lshlrev_b32_e32 v92, 16, v74
	v_and_b32_e32 v93, 0xffff0000, v74
	v_pk_fma_f32 v[80:81], v[46:47], v[92:93], v[80:81]
	v_pk_fma_f32 v[74:75], v[48:49], v[104:105], v[78:79]
	v_pk_mul_f32 v[84:85], v[80:81], s[36:37] op_sel_hi:[1,0]
	v_pk_mul_f32 v[78:79], v[74:75], s[36:37] op_sel_hi:[1,0]
	v_exp_f32_e32 v84, v84
	v_exp_f32_e32 v85, v85
	v_exp_f32_e32 v78, v78
	v_exp_f32_e32 v79, v79
	v_pk_fma_f32 v[82:83], v[30:31], v[90:91], v[82:83]
	v_pk_add_f32 v[84:85], v[84:85], 1.0 op_sel_hi:[1,0]
	v_lshlrev_b32_e32 v94, 16, v76
	v_pk_add_f32 v[78:79], v[78:79], 1.0 op_sel_hi:[1,0]
	v_rcp_f32_e32 v84, v84
	v_rcp_f32_e32 v85, v85
	v_rcp_f32_e32 v78, v78
	v_rcp_f32_e32 v79, v79
	v_and_b32_e32 v95, 0xffff0000, v76
	v_pk_fma_f32 v[82:83], v[22:23], v[94:95], v[82:83]
	v_pk_fma_f32 v[102:103], v[18:19], v[102:103], v[34:35]
	v_pk_mul_f32 v[74:75], v[74:75], v[78:79]
	v_pk_mul_f32 v[78:79], v[80:81], v[84:85]
	v_pk_fma_f32 v[80:81], v[20:21], v[108:109], v[36:37]
	v_pk_mul_f32 v[84:85], v[82:83], s[36:37] op_sel_hi:[1,0]
	v_pk_fma_f32 v[80:81], v[28:29], v[106:107], v[80:81]
	v_exp_f32_e32 v84, v84
	v_pk_fma_f32 v[80:81], v[32:33], v[96:97], v[80:81]
	v_exp_f32_e32 v85, v85
	v_pk_fma_f32 v[76:77], v[24:25], v[132:133], v[80:81]
	v_pk_fma_f32 v[102:103], v[26:27], v[90:91], v[102:103]
	v_pk_mul_f32 v[80:81], v[76:77], s[36:37] op_sel_hi:[1,0]
	v_pk_add_f32 v[84:85], v[84:85], 1.0 op_sel_hi:[1,0]
	v_exp_f32_e32 v80, v80
	v_exp_f32_e32 v81, v81
	v_rcp_f32_e32 v84, v84
	v_rcp_f32_e32 v85, v85
	v_pk_fma_f32 v[90:91], v[18:19], v[90:91], v[34:35]
	v_pk_add_f32 v[80:81], v[80:81], 1.0 op_sel_hi:[1,0]
	v_pk_fma_f32 v[90:91], v[26:27], v[94:95], v[90:91]
	v_rcp_f32_e32 v80, v80
	v_rcp_f32_e32 v81, v81
	s_nop 0
	v_pk_mul_f32 v[76:77], v[76:77], v[80:81]
	v_pk_mul_f32 v[80:81], v[82:83], v[84:85]
	v_pk_fma_f32 v[82:83], v[44:45], v[100:101], v[64:65]
	v_pk_fma_f32 v[84:85], v[42:43], v[98:99], v[62:63]
	v_pk_fma_f32 v[82:83], v[52:53], v[88:89], v[82:83]
	v_pk_fma_f32 v[84:85], v[50:51], v[86:87], v[84:85]
	v_pk_fma_f32 v[82:83], v[56:57], v[104:105], v[82:83]
	v_pk_fma_f32 v[84:85], v[54:55], v[92:93], v[84:85]
	v_lshlrev_b32_e32 v98, 16, v58
	v_and_b32_e32 v99, 0xffff0000, v58
	v_lshlrev_b32_e32 v100, 16, v59
	v_and_b32_e32 v101, 0xffff0000, v59
	v_pk_fma_f32 v[84:85], v[46:47], v[98:99], v[84:85]
	v_pk_fma_f32 v[58:59], v[48:49], v[100:101], v[82:83]
	v_pk_mul_f32 v[108:109], v[84:85], s[36:37] op_sel_hi:[1,0]
	v_pk_mul_f32 v[82:83], v[58:59], s[36:37] op_sel_hi:[1,0]
	v_exp_f32_e32 v108, v108
	v_exp_f32_e32 v109, v109
	v_exp_f32_e32 v82, v82
	v_exp_f32_e32 v83, v83
	v_pk_fma_f32 v[88:89], v[44:45], v[88:89], v[64:65]
	v_pk_add_f32 v[108:109], v[108:109], 1.0 op_sel_hi:[1,0]
	v_pk_fma_f32 v[88:89], v[52:53], v[104:105], v[88:89]
	v_pk_add_f32 v[82:83], v[82:83], 1.0 op_sel_hi:[1,0]
	v_rcp_f32_e32 v108, v108
	v_rcp_f32_e32 v109, v109
	v_rcp_f32_e32 v82, v82
	v_rcp_f32_e32 v83, v83
	v_pk_fma_f32 v[86:87], v[42:43], v[86:87], v[62:63]
	v_pk_fma_f32 v[88:89], v[56:57], v[100:101], v[88:89]
	v_pk_fma_f32 v[86:87], v[50:51], v[92:93], v[86:87]
	v_pk_mul_f32 v[58:59], v[58:59], v[82:83]
	v_pk_mul_f32 v[82:83], v[84:85], v[108:109]
	v_pk_fma_f32 v[84:85], v[20:21], v[106:107], v[36:37]
	v_pk_fma_f32 v[106:107], v[30:31], v[94:95], v[102:103]
	v_pk_fma_f32 v[84:85], v[28:29], v[96:97], v[84:85]
	v_lshlrev_b32_e32 v102, 16, v60
	v_pk_fma_f32 v[84:85], v[32:33], v[132:133], v[84:85]
	v_and_b32_e32 v103, 0xffff0000, v60
	v_pk_fma_f32 v[106:107], v[22:23], v[102:103], v[106:107]
	v_pk_fma_f32 v[60:61], v[24:25], v[130:131], v[84:85]
	v_pk_mul_f32 v[108:109], v[106:107], s[36:37] op_sel_hi:[1,0]
	v_pk_mul_f32 v[84:85], v[60:61], s[36:37] op_sel_hi:[1,0]
	v_exp_f32_e32 v108, v108
	v_exp_f32_e32 v109, v109
	v_exp_f32_e32 v84, v84
	v_exp_f32_e32 v85, v85
	v_pk_fma_f32 v[38:39], v[48:49], v[114:115], v[88:89]
	v_pk_add_f32 v[108:109], v[108:109], 1.0 op_sel_hi:[1,0]
	v_pk_fma_f32 v[86:87], v[54:55], v[98:99], v[86:87]
	v_pk_add_f32 v[84:85], v[84:85], 1.0 op_sel_hi:[1,0]
	v_rcp_f32_e32 v108, v108
	v_rcp_f32_e32 v109, v109
	v_rcp_f32_e32 v84, v84
	v_rcp_f32_e32 v85, v85
	v_pk_mul_f32 v[88:89], v[38:39], s[36:37] op_sel_hi:[1,0]
	v_pk_fma_f32 v[86:87], v[46:47], v[110:111], v[86:87]
	v_exp_f32_e32 v88, v88
	v_exp_f32_e32 v89, v89
	v_pk_mul_f32 v[60:61], v[60:61], v[84:85]
	v_pk_mul_f32 v[84:85], v[106:107], v[108:109]
	v_pk_mul_f32 v[106:107], v[86:87], s[36:37] op_sel_hi:[1,0]
	v_pk_add_f32 v[88:89], v[88:89], 1.0 op_sel_hi:[1,0]
	v_exp_f32_e32 v106, v106
	v_exp_f32_e32 v107, v107
	v_rcp_f32_e32 v88, v88
	v_rcp_f32_e32 v89, v89
	v_pk_fma_f32 v[90:91], v[30:31], v[102:103], v[90:91]
	v_pk_add_f32 v[106:107], v[106:107], 1.0 op_sel_hi:[1,0]
	v_lshlrev_b32_e32 v108, 16, v14
	v_rcp_f32_e32 v106, v106
	v_rcp_f32_e32 v107, v107
	v_pk_mul_f32 v[38:39], v[38:39], v[88:89]
	v_pk_fma_f32 v[88:89], v[20:21], v[96:97], v[36:37]
	v_and_b32_e32 v109, 0xffff0000, v14
	v_pk_fma_f32 v[88:89], v[28:29], v[132:133], v[88:89]
	v_pk_mul_f32 v[86:87], v[86:87], v[106:107]
	v_pk_fma_f32 v[88:89], v[32:33], v[130:131], v[88:89]
	v_lshlrev_b32_e32 v106, 16, v40
	v_and_b32_e32 v107, 0xffff0000, v40
	v_pk_fma_f32 v[90:91], v[22:23], v[106:107], v[90:91]
	v_pk_fma_f32 v[40:41], v[24:25], v[116:117], v[88:89]
	v_pk_mul_f32 v[96:97], v[90:91], s[36:37] op_sel_hi:[1,0]
	v_pk_mul_f32 v[88:89], v[40:41], s[36:37] op_sel_hi:[1,0]
	v_exp_f32_e32 v96, v96
	v_exp_f32_e32 v97, v97
	v_exp_f32_e32 v88, v88
	v_exp_f32_e32 v89, v89
	v_pk_fma_f32 v[94:95], v[18:19], v[94:95], v[34:35]
	v_pk_add_f32 v[96:97], v[96:97], 1.0 op_sel_hi:[1,0]
	v_pk_fma_f32 v[94:95], v[26:27], v[102:103], v[94:95]
	v_pk_add_f32 v[88:89], v[88:89], 1.0 op_sel_hi:[1,0]
	v_rcp_f32_e32 v96, v96
	v_rcp_f32_e32 v97, v97
	v_rcp_f32_e32 v88, v88
	v_rcp_f32_e32 v89, v89
	v_pk_fma_f32 v[94:95], v[30:31], v[106:107], v[94:95]
	v_pk_fma_f32 v[102:103], v[18:19], v[102:103], v[34:35]
	v_pk_mul_f32 v[40:41], v[40:41], v[88:89]
	v_pk_mul_f32 v[88:89], v[90:91], v[96:97]
	v_pk_fma_f32 v[90:91], v[42:43], v[92:93], v[62:63]
	v_pk_fma_f32 v[92:93], v[44:45], v[104:105], v[64:65]
	v_pk_fma_f32 v[90:91], v[50:51], v[98:99], v[90:91]
	v_pk_fma_f32 v[92:93], v[52:53], v[100:101], v[92:93]
	v_pk_fma_f32 v[90:91], v[54:55], v[110:111], v[90:91]
	v_pk_fma_f32 v[92:93], v[56:57], v[114:115], v[92:93]
	v_pk_fma_f32 v[100:101], v[44:45], v[100:101], v[64:65]
	v_pk_fma_f32 v[14:15], v[48:49], v[112:113], v[92:93]
	v_pk_fma_f32 v[92:93], v[46:47], v[108:109], v[90:91]
	v_pk_mul_f32 v[90:91], v[14:15], s[36:37] op_sel_hi:[1,0]
	v_pk_mul_f32 v[96:97], v[92:93], s[36:37] op_sel_hi:[1,0]
	v_exp_f32_e32 v90, v90
	v_exp_f32_e32 v91, v91
	v_exp_f32_e32 v96, v96
	v_exp_f32_e32 v97, v97
	v_pk_fma_f32 v[98:99], v[42:43], v[98:99], v[62:63]
	v_pk_add_f32 v[90:91], v[90:91], 1.0 op_sel_hi:[1,0]
	v_pk_fma_f32 v[100:101], v[52:53], v[114:115], v[100:101]
	v_rcp_f32_e32 v90, v90
	v_rcp_f32_e32 v91, v91
	v_pk_add_f32 v[96:97], v[96:97], 1.0 op_sel_hi:[1,0]
	v_pk_fma_f32 v[98:99], v[50:51], v[110:111], v[98:99]
	v_rcp_f32_e32 v96, v96
	v_rcp_f32_e32 v97, v97
	v_pk_mul_f32 v[90:91], v[14:15], v[90:91]
	v_pk_fma_f32 v[14:15], v[20:21], v[132:133], v[36:37]
	v_pk_fma_f32 v[100:101], v[56:57], v[112:113], v[100:101]
	v_pk_fma_f32 v[14:15], v[28:29], v[130:131], v[14:15]
	v_pk_mul_f32 v[92:93], v[92:93], v[96:97]
	v_pk_fma_f32 v[96:97], v[32:33], v[116:117], v[14:15]
	v_lshlrev_b32_e32 v14, 16, v16
	v_and_b32_e32 v15, 0xffff0000, v16
	v_lshlrev_b32_e32 v16, 16, v17
	v_and_b32_e32 v17, 0xffff0000, v17
	v_pk_fma_f32 v[104:105], v[22:23], v[14:15], v[94:95]
	v_pk_fma_f32 v[94:95], v[24:25], v[16:17], v[96:97]
	v_pk_mul_f32 v[132:133], v[104:105], s[36:37] op_sel_hi:[1,0]
	v_pk_mul_f32 v[96:97], v[94:95], s[36:37] op_sel_hi:[1,0]
	v_exp_f32_e32 v132, v132
	v_exp_f32_e32 v133, v133
	v_exp_f32_e32 v96, v96
	v_exp_f32_e32 v97, v97
	v_pk_fma_f32 v[98:99], v[54:55], v[108:109], v[98:99]
	v_pk_add_f32 v[132:133], v[132:133], 1.0 op_sel_hi:[1,0]
	v_pk_fma_f32 v[102:103], v[26:27], v[106:107], v[102:103]
	v_pk_add_f32 v[96:97], v[96:97], 1.0 op_sel_hi:[1,0]
	v_rcp_f32_e32 v132, v132
	v_rcp_f32_e32 v133, v133
	v_rcp_f32_e32 v96, v96
	v_rcp_f32_e32 v97, v97
	v_pk_fma_f32 v[102:103], v[30:31], v[14:15], v[102:103]
	v_pk_fma_f32 v[114:115], v[44:45], v[114:115], v[64:65]
	v_pk_fma_f32 v[110:111], v[42:43], v[110:111], v[62:63]
	v_pk_mul_f32 v[94:95], v[94:95], v[96:97]
	v_pk_mul_f32 v[96:97], v[104:105], v[132:133]
	v_lshlrev_b32_e32 v132, 16, v10
	v_and_b32_e32 v133, 0xffff0000, v10
	v_pk_fma_f32 v[10:11], v[48:49], v[134:135], v[100:101]
	v_pk_fma_f32 v[100:101], v[46:47], v[132:133], v[98:99]
	v_pk_mul_f32 v[98:99], v[10:11], s[36:37] op_sel_hi:[1,0]
	v_pk_mul_f32 v[104:105], v[100:101], s[36:37] op_sel_hi:[1,0]
	v_exp_f32_e32 v98, v98
	v_exp_f32_e32 v99, v99
	v_exp_f32_e32 v104, v104
	v_exp_f32_e32 v105, v105
	v_pk_fma_f32 v[114:115], v[52:53], v[112:113], v[114:115]
	v_pk_add_f32 v[98:99], v[98:99], 1.0 op_sel_hi:[1,0]
	v_pk_fma_f32 v[42:43], v[42:43], v[108:109], v[62:63]
	v_rcp_f32_e32 v98, v98
	v_rcp_f32_e32 v99, v99
	v_pk_add_f32 v[104:105], v[104:105], 1.0 op_sel_hi:[1,0]
	v_pk_fma_f32 v[44:45], v[44:45], v[112:113], v[64:65]
	v_rcp_f32_e32 v104, v104
	v_rcp_f32_e32 v105, v105
	v_pk_mul_f32 v[98:99], v[10:11], v[98:99]
	v_pk_fma_f32 v[10:11], v[20:21], v[130:131], v[36:37]
	v_pk_fma_f32 v[114:115], v[56:57], v[134:135], v[114:115]
	v_pk_fma_f32 v[10:11], v[28:29], v[116:117], v[10:11]
	v_pk_mul_f32 v[100:101], v[100:101], v[104:105]
	v_pk_fma_f32 v[104:105], v[32:33], v[16:17], v[10:11]
	v_lshlrev_b32_e32 v10, 16, v12
	v_and_b32_e32 v11, 0xffff0000, v12
	v_lshlrev_b32_e32 v12, 16, v13
	v_and_b32_e32 v13, 0xffff0000, v13
	v_pk_fma_f32 v[130:131], v[22:23], v[10:11], v[102:103]
	v_pk_fma_f32 v[102:103], v[24:25], v[12:13], v[104:105]
	v_pk_mul_f32 v[146:147], v[130:131], s[36:37] op_sel_hi:[1,0]
	v_pk_mul_f32 v[104:105], v[102:103], s[36:37] op_sel_hi:[1,0]
	v_exp_f32_e32 v146, v146
	v_exp_f32_e32 v147, v147
	v_exp_f32_e32 v104, v104
	v_exp_f32_e32 v105, v105
	v_pk_fma_f32 v[44:45], v[52:53], v[134:135], v[44:45]
	v_pk_add_f32 v[146:147], v[146:147], 1.0 op_sel_hi:[1,0]
	v_pk_fma_f32 v[42:43], v[50:51], v[132:133], v[42:43]
	v_pk_add_f32 v[104:105], v[104:105], 1.0 op_sel_hi:[1,0]
	v_rcp_f32_e32 v146, v146
	v_rcp_f32_e32 v147, v147
	v_rcp_f32_e32 v104, v104
	v_rcp_f32_e32 v105, v105
	v_pk_fma_f32 v[110:111], v[50:51], v[108:109], v[110:111]
	v_pk_fma_f32 v[116:117], v[20:21], v[116:117], v[36:37]
	v_pk_fma_f32 v[110:111], v[54:55], v[132:133], v[110:111]
	v_pk_mul_f32 v[102:103], v[102:103], v[104:105]
	v_pk_mul_f32 v[104:105], v[130:131], v[146:147]
	v_lshlrev_b32_e32 v130, 16, v6
	v_and_b32_e32 v131, 0xffff0000, v6
	v_lshlrev_b32_e32 v6, 16, v7
	v_and_b32_e32 v7, 0xffff0000, v7
	v_pk_fma_f32 v[114:115], v[48:49], v[6:7], v[114:115]
	v_pk_fma_f32 v[6:7], v[56:57], v[6:7], v[44:45]
	v_pk_fma_f32 v[42:43], v[54:55], v[130:131], v[42:43]
	v_lshlrev_b32_e32 v44, 16, v2
	v_and_b32_e32 v45, 0xffff0000, v2
	v_lshlrev_b32_e32 v2, 16, v3
	v_and_b32_e32 v3, 0xffff0000, v3
	v_pk_fma_f32 v[2:3], v[48:49], v[2:3], v[6:7]
	v_pk_fma_f32 v[6:7], v[46:47], v[44:45], v[42:43]
	v_pk_fma_f32 v[146:147], v[46:47], v[130:131], v[110:111]
	v_pk_mul_f32 v[42:43], v[2:3], s[36:37] op_sel_hi:[1,0]
	v_pk_mul_f32 v[44:45], v[6:7], s[36:37] op_sel_hi:[1,0]
	v_pk_mul_f32 v[110:111], v[114:115], s[36:37] op_sel_hi:[1,0]
	v_pk_mul_f32 v[160:161], v[146:147], s[36:37] op_sel_hi:[1,0]
	v_exp_f32_e32 v44, v44
	v_exp_f32_e32 v45, v45
	v_exp_f32_e32 v42, v42
	v_exp_f32_e32 v43, v43
	v_exp_f32_e32 v160, v160
	v_exp_f32_e32 v161, v161
	v_exp_f32_e32 v110, v110
	v_exp_f32_e32 v111, v111
	v_pk_add_f32 v[42:43], v[42:43], 1.0 op_sel_hi:[1,0]
	v_pk_add_f32 v[44:45], v[44:45], 1.0 op_sel_hi:[1,0]
	v_pk_add_f32 v[160:161], v[160:161], 1.0 op_sel_hi:[1,0]
	v_pk_add_f32 v[110:111], v[110:111], 1.0 op_sel_hi:[1,0]
	v_rcp_f32_e32 v44, v44
	v_rcp_f32_e32 v45, v45
	v_rcp_f32_e32 v42, v42
	v_rcp_f32_e32 v43, v43
	v_rcp_f32_e32 v160, v160
	v_rcp_f32_e32 v161, v161
	v_rcp_f32_e32 v110, v110
	v_rcp_f32_e32 v111, v111
	v_pk_fma_f32 v[106:107], v[18:19], v[106:107], v[34:35]
	v_pk_fma_f32 v[116:117], v[28:29], v[16:17], v[116:117]
	v_pk_fma_f32 v[106:107], v[26:27], v[14:15], v[106:107]
	v_pk_mul_f32 v[42:43], v[2:3], v[42:43]
	v_pk_mul_f32 v[44:45], v[6:7], v[44:45]
	v_pk_fma_f32 v[2:3], v[20:21], v[16:17], v[36:37]
	v_pk_fma_f32 v[6:7], v[18:19], v[14:15], v[34:35]
	v_pk_mul_f32 v[110:111], v[114:115], v[110:111]
	v_pk_mul_f32 v[114:115], v[146:147], v[160:161]
	v_pk_fma_f32 v[116:117], v[32:33], v[12:13], v[116:117]
	v_pk_fma_f32 v[106:107], v[30:31], v[10:11], v[106:107]
	v_lshlrev_b32_e32 v146, 16, v8
	v_and_b32_e32 v147, 0xffff0000, v8
	v_lshlrev_b32_e32 v8, 16, v9
	v_and_b32_e32 v9, 0xffff0000, v9
	v_pk_fma_f32 v[6:7], v[26:27], v[10:11], v[6:7]
	v_pk_fma_f32 v[2:3], v[28:29], v[12:13], v[2:3]
	v_pk_fma_f32 v[160:161], v[22:23], v[146:147], v[106:107]
	v_pk_fma_f32 v[106:107], v[24:25], v[8:9], v[116:117]
	v_pk_fma_f32 v[2:3], v[32:33], v[8:9], v[2:3]
	v_pk_fma_f32 v[6:7], v[30:31], v[146:147], v[6:7]
	v_lshlrev_b32_e32 v8, 16, v4
	v_and_b32_e32 v9, 0xffff0000, v4
	v_lshlrev_b32_e32 v4, 16, v5
	v_and_b32_e32 v5, 0xffff0000, v5
	v_pk_fma_f32 v[6:7], v[22:23], v[8:9], v[6:7]
	v_pk_fma_f32 v[2:3], v[24:25], v[4:5], v[2:3]
	v_pk_mul_f32 v[8:9], v[6:7], s[36:37] op_sel_hi:[1,0]
	v_pk_mul_f32 v[4:5], v[2:3], s[36:37] op_sel_hi:[1,0]
	v_exp_f32_e32 v8, v8
	v_exp_f32_e32 v9, v9
	v_exp_f32_e32 v4, v4
	v_exp_f32_e32 v5, v5
	v_mul_f32_e32 v10, v137, v69
	v_pk_add_f32 v[8:9], v[8:9], 1.0 op_sel_hi:[1,0]
	v_mul_f32_e32 v11, v138, v79
	v_pk_add_f32 v[4:5], v[4:5], 1.0 op_sel_hi:[1,0]
	v_rcp_f32_e32 v8, v8
	v_rcp_f32_e32 v9, v9
	v_rcp_f32_e32 v4, v4
	v_rcp_f32_e32 v5, v5
	v_mul_f32_e32 v12, v138, v75
	v_pk_mul_f32 v[36:37], v[6:7], v[8:9]
	v_mul_f32_e32 v6, v137, v70
	v_mul_f32_e32 v7, v137, v71
	v_pk_mul_f32 v[46:47], v[2:3], v[4:5]
	v_cvt_pk_bf16_f32 v2, v70, v71
	v_cvt_pk_bf16_f32 v3, v66, v67
	v_cvt_pk_bf16_f32 v4, v72, v73
	v_cvt_pk_bf16_f32 v5, v68, v69
	v_cvt_pk_bf16_f32 v6, v6, v7
	v_mul_f32_e32 v7, v137, v66
	v_mul_f32_e32 v8, v137, v67
	v_cvt_pk_bf16_f32 v7, v7, v8
	v_mul_f32_e32 v8, v137, v72
	v_mul_f32_e32 v9, v137, v73
	v_cvt_pk_bf16_f32 v8, v8, v9
	v_mul_f32_e32 v9, v137, v68
	v_cvt_pk_bf16_f32 v9, v9, v10
	v_mul_f32_e32 v10, v138, v78
	ds_write_b128 v156, v[6:9]
	v_cvt_pk_bf16_f32 v6, v78, v79
	v_cvt_pk_bf16_f32 v7, v74, v75
	v_cvt_pk_bf16_f32 v8, v80, v81
	v_cvt_pk_bf16_f32 v9, v76, v77
	v_cvt_pk_bf16_f32 v10, v10, v11
	v_mul_f32_e32 v11, v138, v74
	v_cvt_pk_bf16_f32 v11, v11, v12
	v_mul_f32_e32 v12, v138, v80
	v_mul_f32_e32 v13, v138, v81
	v_cvt_pk_bf16_f32 v12, v12, v13
	v_mul_f32_e32 v13, v138, v76
	v_mul_f32_e32 v14, v138, v77
	v_cvt_pk_bf16_f32 v13, v13, v14
	v_mul_f32_e32 v14, v139, v82
	v_mul_f32_e32 v15, v139, v83
	ds_write_b128 v156, v[10:13] offset:64
	v_cvt_pk_bf16_f32 v10, v82, v83
	v_cvt_pk_bf16_f32 v11, v58, v59
	v_cvt_pk_bf16_f32 v12, v84, v85
	v_cvt_pk_bf16_f32 v13, v60, v61
	v_cvt_pk_bf16_f32 v14, v14, v15
	v_mul_f32_e32 v15, v139, v58
	v_mul_f32_e32 v16, v139, v59
	v_cvt_pk_bf16_f32 v15, v15, v16
	v_mul_f32_e32 v16, v139, v84
	v_mul_f32_e32 v17, v139, v85
	v_cvt_pk_bf16_f32 v16, v16, v17
	v_mul_f32_e32 v17, v139, v60
	v_mul_f32_e32 v18, v139, v61
	v_cvt_pk_bf16_f32 v17, v17, v18
	v_mul_f32_e32 v18, v140, v86
	v_mul_f32_e32 v19, v140, v87
	ds_write_b128 v156, v[14:17] offset:128
	v_cvt_pk_bf16_f32 v14, v86, v87
	v_cvt_pk_bf16_f32 v15, v38, v39
	v_cvt_pk_bf16_f32 v16, v88, v89
	v_cvt_pk_bf16_f32 v17, v40, v41
	v_cvt_pk_bf16_f32 v18, v18, v19
	v_mul_f32_e32 v19, v140, v38
	v_mul_f32_e32 v20, v140, v39
	v_cvt_pk_bf16_f32 v19, v19, v20
	v_mul_f32_e32 v20, v140, v88
	v_mul_f32_e32 v21, v140, v89
	v_pk_mul_f32 v[116:117], v[106:107], s[36:37] op_sel_hi:[1,0]
	v_pk_mul_f32 v[162:163], v[160:161], s[36:37] op_sel_hi:[1,0]
	v_cvt_pk_bf16_f32 v20, v20, v21
	v_mul_f32_e32 v21, v140, v40
	v_mul_f32_e32 v22, v140, v41
	v_exp_f32_e32 v162, v162
	v_exp_f32_e32 v163, v163
	v_exp_f32_e32 v116, v116
	v_exp_f32_e32 v117, v117
	v_cvt_pk_bf16_f32 v21, v21, v22
	v_mul_f32_e32 v22, v141, v92
	v_mul_f32_e32 v23, v141, v93
	ds_write_b128 v156, v[18:21] offset:192
	v_cvt_pk_bf16_f32 v18, v92, v93
	v_cvt_pk_bf16_f32 v19, v90, v91
	v_cvt_pk_bf16_f32 v20, v96, v97
	v_cvt_pk_bf16_f32 v21, v94, v95
	v_cvt_pk_bf16_f32 v22, v22, v23
	v_mul_f32_e32 v23, v141, v90
	v_mul_f32_e32 v24, v141, v91
	v_cvt_pk_bf16_f32 v23, v23, v24
	v_mul_f32_e32 v24, v141, v96
	v_mul_f32_e32 v25, v141, v97
	v_cvt_pk_bf16_f32 v24, v24, v25
	v_mul_f32_e32 v25, v141, v94
	v_mul_f32_e32 v26, v141, v95
	v_pk_add_f32 v[116:117], v[116:117], 1.0 op_sel_hi:[1,0]
	v_pk_add_f32 v[162:163], v[162:163], 1.0 op_sel_hi:[1,0]
	v_cvt_pk_bf16_f32 v25, v25, v26
	v_mul_f32_e32 v26, v142, v100
	v_mul_f32_e32 v27, v142, v101
	v_rcp_f32_e32 v162, v162
	v_rcp_f32_e32 v163, v163
	v_rcp_f32_e32 v116, v116
	v_rcp_f32_e32 v117, v117
	ds_write_b128 v156, v[22:25] offset:256
	v_cvt_pk_bf16_f32 v22, v100, v101
	v_cvt_pk_bf16_f32 v23, v98, v99
	v_cvt_pk_bf16_f32 v24, v104, v105
	v_cvt_pk_bf16_f32 v25, v102, v103
	v_cvt_pk_bf16_f32 v26, v26, v27
	v_mul_f32_e32 v27, v142, v98
	v_mul_f32_e32 v28, v142, v99
	v_cvt_pk_bf16_f32 v27, v27, v28
	v_mul_f32_e32 v28, v142, v104
	v_mul_f32_e32 v29, v142, v105
	v_cvt_pk_bf16_f32 v28, v28, v29
	v_mul_f32_e32 v29, v142, v102
	v_mul_f32_e32 v30, v142, v103
	v_cvt_pk_bf16_f32 v29, v29, v30
	v_mul_f32_e32 v30, v143, v114
	v_mul_f32_e32 v31, v143, v115
	v_pk_mul_f32 v[106:107], v[106:107], v[116:117]
	v_pk_mul_f32 v[116:117], v[160:161], v[162:163]
	ds_write_b128 v156, v[26:29] offset:320
	v_cvt_pk_bf16_f32 v26, v114, v115
	v_cvt_pk_bf16_f32 v27, v110, v111
	v_cvt_pk_bf16_f32 v28, v116, v117
	v_cvt_pk_bf16_f32 v29, v106, v107
	v_cvt_pk_bf16_f32 v30, v30, v31
	v_mul_f32_e32 v31, v143, v110
	v_mul_f32_e32 v32, v143, v111
	v_cvt_pk_bf16_f32 v31, v31, v32
	v_mul_f32_e32 v32, v143, v116
	v_mul_f32_e32 v33, v143, v117
	v_cvt_pk_bf16_f32 v32, v32, v33
	v_mul_f32_e32 v33, v143, v106
	v_mul_f32_e32 v34, v143, v107
	v_cvt_pk_bf16_f32 v33, v33, v34
	v_mul_f32_e32 v34, v144, v44
	v_mul_f32_e32 v35, v144, v45
	ds_write_b128 v156, v[30:33] offset:384
	v_cvt_pk_bf16_f32 v30, v44, v45
	v_cvt_pk_bf16_f32 v31, v42, v43
	v_cvt_pk_bf16_f32 v32, v36, v37
	v_cvt_pk_bf16_f32 v33, v46, v47
	v_cvt_pk_bf16_f32 v34, v34, v35
	v_mul_f32_e32 v35, v144, v42
	v_mul_f32_e32 v36, v144, v36
	v_mul_f32_e32 v37, v144, v37
	v_mul_f32_e32 v38, v144, v43
	v_cvt_pk_bf16_f32 v35, v35, v38
	v_cvt_pk_bf16_f32 v36, v36, v37
	v_mul_f32_e32 v37, v144, v46
	v_mul_f32_e32 v38, v144, v47
	v_cvt_pk_bf16_f32 v37, v37, v38
	ds_write_b128 v156, v[34:37] offset:448
	v_or_b32_e32 v36, s65, v152
	v_lshl_add_u64 v[34:35], s[46:47], 0, v[120:121]
	v_lshlrev_b32_e32 v36, 13, v36
	s_and_saveexec_b64 s[0:1], s[8:9]
	s_xor_b64 s[2:3], exec, s[0:1]
	s_cbranch_execz .LBB0_1379
	v_mov_b32_e32 v37, v121
	v_lshl_add_u64 v[38:39], v[34:35], 0, v[36:37]
	v_add_co_u32_e32 v38, vcc, 0xffffa000, v38
	s_nop 1
	v_addc_co_u32_e32 v39, vcc, -1, v39, vcc
	v_mov_b32_e32 v86, v228
	v_mov_b32_e32 v87, v229
	v_mov_b32_e32 v88, v230
	v_mov_b32_e32 v89, v231
	s_or_saveexec_b64 s[2:3], s[2:3]
	v_lshl_add_u64 v[38:39], s[44:45], 0, v[120:121]
	s_xor_b64 exec, exec, s[2:3]
	s_cbranch_execz .LBB0_1382
	s_branch .LBB0_1380

.LBB0_1380:
	s_and_b64 vcc, exec, s[12:13]
	s_cbranch_vccnz .LBB0_1384
	v_mov_b32_e32 v86, v228
	v_mov_b32_e32 v87, v229
	v_mov_b32_e32 v88, v230
	v_mov_b32_e32 v89, v231

.LBB0_1383:
	v_mov_b32_e32 v37, v121
	v_lshl_add_u64 v[40:41], v[34:35], 0, v[36:37]
	v_add_co_u32_e32 v40, vcc, 0xffffc000, v40
	s_nop 1
	v_addc_co_u32_e32 v41, vcc, -1, v41, vcc
	v_mov_b32_e32 v106, v232
	v_mov_b32_e32 v107, v233
	v_mov_b32_e32 v108, v234
	v_mov_b32_e32 v109, v235
	s_andn2_saveexec_b64 s[2:3], s[2:3]
	s_cbranch_execz .LBB0_1388
	s_branch .LBB0_1386

.LBB0_1386:
	s_and_b64 vcc, exec, s[12:13]
	s_cbranch_vccnz .LBB0_1390
	v_add_co_u32_e32 v40, vcc, 0x2000, v38
	s_nop 1
	v_addc_co_u32_e32 v41, vcc, 0, v39, vcc
	v_mov_b32_e32 v106, v232
	v_mov_b32_e32 v107, v233
	v_mov_b32_e32 v108, v234
	v_mov_b32_e32 v109, v235

.LBB0_1389:
	v_mov_b32_e32 v37, v121
	v_lshl_add_u64 v[38:39], v[34:35], 0, v[36:37]
	v_add_co_u32_e32 v38, vcc, 0xffffe000, v38
	s_nop 1
	v_addc_co_u32_e32 v39, vcc, -1, v39, vcc
	v_mov_b32_e32 v110, v236
	v_mov_b32_e32 v111, v237
	v_mov_b32_e32 v112, v238
	v_mov_b32_e32 v113, v239
	s_andn2_saveexec_b64 s[2:3], s[2:3]
	s_cbranch_execz .LBB0_1395
	s_branch .LBB0_1392

.LBB0_1392:
	s_and_b64 vcc, exec, s[12:13]
	s_cbranch_vccnz .LBB0_1394
	v_add_co_u32_e32 v38, vcc, 0x4000, v38
	s_nop 1
	v_addc_co_u32_e32 v39, vcc, 0, v39, vcc
	v_mov_b32_e32 v110, v236
	v_mov_b32_e32 v111, v237
	v_mov_b32_e32 v112, v238
	v_mov_b32_e32 v113, v239
	s_branch .LBB0_1395

.LBB0_1395:
	s_or_b64 exec, exec, s[2:3]
	v_mov_b32_e32 v37, v121
	v_lshl_add_u64 v[130:131], v[34:35], 0, v[36:37]
	v_add_co_u32_e32 v34, vcc, 0x2000, v130
	v_mov_b32_e32 v114, v196
	v_mov_b32_e32 v115, v197
	v_mov_b32_e32 v116, v198
	v_mov_b32_e32 v117, v199
	s_nop 0
	v_addc_co_u32_e32 v35, vcc, 0, v131, vcc
	v_mov_b32_e32 v94, v200
	v_mov_b32_e32 v95, v201
	v_mov_b32_e32 v96, v202
	v_mov_b32_e32 v97, v203
	v_add_co_u32_e32 v34, vcc, 0x4000, v130
	v_readlane_b32 s80, v254, 34
	s_nop 0
	v_addc_co_u32_e32 v35, vcc, 0, v131, vcc
	v_mov_b32_e32 v102, v204
	v_mov_b32_e32 v103, v205
	v_mov_b32_e32 v104, v206
	v_mov_b32_e32 v105, v207
	v_add_co_u32_e32 v34, vcc, s57, v130
	v_readlane_b32 s92, v254, 46
	s_nop 0
	v_addc_co_u32_e32 v35, vcc, 0, v131, vcc
	v_mov_b32_e32 v98, v208
	v_mov_b32_e32 v99, v209
	v_mov_b32_e32 v100, v210
	v_mov_b32_e32 v101, v211
	v_add_co_u32_e32 v34, vcc, 0x8000, v130
	v_readlane_b32 s93, v254, 47
	s_nop 0
	v_addc_co_u32_e32 v35, vcc, 0, v131, vcc
	v_mov_b32_e32 v90, v212
	v_mov_b32_e32 v91, v213
	v_mov_b32_e32 v92, v214
	v_mov_b32_e32 v93, v215
	v_add_co_u32_e32 v34, vcc, 0xa000, v130
	v_lshlrev_b32_e32 v120, 2, v136
	s_nop 0
	v_addc_co_u32_e32 v35, vcc, 0, v131, vcc
	v_mov_b32_e32 v82, v216
	v_mov_b32_e32 v83, v217
	v_mov_b32_e32 v84, v218
	v_mov_b32_e32 v85, v219
	v_add_co_u32_e32 v34, vcc, 0xc000, v130
	v_readlane_b32 s94, v254, 48
	s_nop 0
	v_addc_co_u32_e32 v35, vcc, 0, v131, vcc
	v_mov_b32_e32 v74, v220
	v_mov_b32_e32 v75, v221
	v_mov_b32_e32 v76, v222
	v_mov_b32_e32 v77, v223
	v_add_co_u32_e32 v34, vcc, s56, v130
	v_readlane_b32 s95, v254, 49
	s_mov_b64 s[68:69], s[92:93]
	v_addc_co_u32_e32 v35, vcc, 0, v131, vcc
	v_lshl_add_u64 v[46:47], s[68:69], 0, v[120:121]
	v_add_co_u32_e32 v44, vcc, s58, v46
	v_lshl_add_u64 v[42:43], v[46:47], 0, s[22:23]
	s_nop 0
	v_addc_co_u32_e32 v45, vcc, 0, v47, vcc
	v_add_co_u32_e32 v50, vcc, s59, v46
	v_lshl_add_u64 v[48:49], v[46:47], 0, s[26:27]
	s_nop 0
	v_addc_co_u32_e32 v51, vcc, 0, v47, vcc
	v_mov_b32_e32 v34, v224
	v_mov_b32_e32 v35, v225
	v_mov_b32_e32 v36, v226
	v_mov_b32_e32 v37, v227
	s_nop 0
	global_load_dwordx4 v[38:41], v120, s[68:69] offset:16
	global_load_dwordx4 v[58:61], v120, s[68:69]
	global_load_dwordx4 v[62:65], v[44:45], off
	s_nop 0
	global_load_dwordx4 v[42:45], v[42:43], off offset:16
	s_nop 0
	global_load_dwordx4 v[70:73], v[50:51], off
	s_nop 0
	global_load_dwordx4 v[50:53], v[48:49], off offset:16
	v_lshl_add_u64 v[48:49], v[46:47], 0, s[30:31]
	v_add_co_u32_e32 v46, vcc, s60, v46
	s_mov_b64 s[70:71], s[94:95]
	s_nop 0
	v_addc_co_u32_e32 v47, vcc, 0, v47, vcc
	global_load_dwordx4 v[66:69], v[46:47], off
	s_nop 0
	global_load_dwordx4 v[46:49], v[48:49], off offset:16
	s_nop 0
	global_load_dwordx4 v[54:57], v120, s[70:71] offset:16
	global_load_dwordx4 v[78:81], v120, s[70:71]
	s_waitcnt vmcnt(10)
	v_lshlrev_b32_e32 v132, 16, v86
	v_and_b32_e32 v133, 0xffff0000, v86
	v_lshlrev_b32_e32 v86, 16, v87
	v_and_b32_e32 v87, 0xffff0000, v87
	v_lshlrev_b32_e32 v136, 16, v106
	v_and_b32_e32 v137, 0xffff0000, v106
	v_lshlrev_b32_e32 v140, 16, v107
	v_and_b32_e32 v141, 0xffff0000, v107
	v_lshlrev_b32_e32 v134, 16, v111
	v_and_b32_e32 v135, 0xffff0000, v111
	v_lshlrev_b32_e32 v144, 16, v109
	v_and_b32_e32 v145, 0xffff0000, v109
	v_readlane_b32 s81, v254, 35
	v_readlane_b32 s82, v254, 36
	v_readlane_b32 s83, v254, 37
	v_readlane_b32 s84, v254, 38
	v_readlane_b32 s85, v254, 39
	v_readlane_b32 s86, v254, 40
	s_waitcnt vmcnt(10)
	v_and_b32_e32 v111, 0xffff0000, v115
	v_readlane_b32 s87, v254, 41
	v_readlane_b32 s88, v254, 42
	v_readlane_b32 s89, v254, 43
	v_readlane_b32 s90, v254, 44
	v_readlane_b32 s91, v254, 45
	s_waitcnt vmcnt(0)
	v_pk_fma_f32 v[86:87], v[60:61], v[86:87], v[80:81]
	v_pk_fma_f32 v[132:133], v[58:59], v[132:133], v[78:79]
	v_pk_fma_f32 v[86:87], v[64:65], v[140:141], v[86:87]
	v_pk_fma_f32 v[106:107], v[62:63], v[136:137], v[132:133]
	v_lshlrev_b32_e32 v132, 16, v110
	v_and_b32_e32 v133, 0xffff0000, v110
	v_pk_fma_f32 v[86:87], v[72:73], v[134:135], v[86:87]
	v_pk_fma_f32 v[138:139], v[70:71], v[132:133], v[106:107]
	v_lshlrev_b32_e32 v106, 16, v114
	v_and_b32_e32 v107, 0xffff0000, v114
	v_lshlrev_b32_e32 v110, 16, v115
	v_pk_fma_f32 v[114:115], v[66:67], v[106:107], v[138:139]
	v_pk_fma_f32 v[86:87], v[68:69], v[110:111], v[86:87]
	v_pk_mul_f32 v[142:143], v[114:115], s[36:37] op_sel_hi:[1,0]
	v_pk_mul_f32 v[138:139], v[86:87], s[36:37] op_sel_hi:[1,0]
	v_exp_f32_e32 v142, v142
	v_exp_f32_e32 v143, v143
	v_exp_f32_e32 v138, v138
	v_exp_f32_e32 v139, v139
	v_pk_add_f32 v[142:143], v[142:143], 1.0 op_sel_hi:[1,0]
	s_nop 0
	v_rcp_f32_e32 v142, v142
	v_pk_add_f32 v[138:139], v[138:139], 1.0 op_sel_hi:[1,0]
	v_rcp_f32_e32 v143, v143
	v_rcp_f32_e32 v138, v138
	v_rcp_f32_e32 v139, v139
	s_nop 0
	v_pk_mul_f32 v[146:147], v[86:87], v[138:139]
	v_pk_mul_f32 v[86:87], v[114:115], v[142:143]
	v_lshlrev_b32_e32 v114, 16, v88
	v_and_b32_e32 v115, 0xffff0000, v88
	v_lshlrev_b32_e32 v88, 16, v89
	v_and_b32_e32 v89, 0xffff0000, v89
	v_pk_fma_f32 v[88:89], v[40:41], v[88:89], v[56:57]
	v_pk_fma_f32 v[138:139], v[38:39], v[114:115], v[54:55]
	v_lshlrev_b32_e32 v114, 16, v108
	v_and_b32_e32 v115, 0xffff0000, v108
	v_pk_fma_f32 v[88:89], v[44:45], v[144:145], v[88:89]
	v_pk_fma_f32 v[108:109], v[42:43], v[114:115], v[138:139]
	v_lshlrev_b32_e32 v138, 16, v112
	v_and_b32_e32 v139, 0xffff0000, v112
	v_lshlrev_b32_e32 v142, 16, v113
	v_and_b32_e32 v143, 0xffff0000, v113
	v_pk_fma_f32 v[88:89], v[52:53], v[142:143], v[88:89]
	v_pk_fma_f32 v[160:161], v[50:51], v[138:139], v[108:109]
	v_lshlrev_b32_e32 v108, 16, v116
	v_and_b32_e32 v109, 0xffff0000, v116
	v_lshlrev_b32_e32 v112, 16, v117
	v_and_b32_e32 v113, 0xffff0000, v117
	v_pk_fma_f32 v[88:89], v[48:49], v[112:113], v[88:89]
	v_pk_fma_f32 v[116:117], v[46:47], v[108:109], v[160:161]
	v_pk_mul_f32 v[160:161], v[88:89], s[36:37] op_sel_hi:[1,0]
	v_pk_mul_f32 v[162:163], v[116:117], s[36:37] op_sel_hi:[1,0]
	v_exp_f32_e32 v160, v160
	v_exp_f32_e32 v162, v162
	v_exp_f32_e32 v163, v163
	v_exp_f32_e32 v161, v161
	v_cvt_pk_bf16_f32 v86, v86, v87
	v_cvt_pk_bf16_f32 v87, v146, v147
	v_pk_add_f32 v[162:163], v[162:163], 1.0 op_sel_hi:[1,0]
	v_pk_add_f32 v[160:161], v[160:161], 1.0 op_sel_hi:[1,0]
	v_rcp_f32_e32 v162, v162
	v_rcp_f32_e32 v163, v163
	v_rcp_f32_e32 v160, v160
	v_rcp_f32_e32 v161, v161
	s_nop 0
	v_pk_mul_f32 v[160:161], v[88:89], v[160:161]
	v_pk_mul_f32 v[88:89], v[116:117], v[162:163]
	s_nop 0
	v_cvt_pk_bf16_f32 v88, v88, v89
	v_cvt_pk_bf16_f32 v89, v160, v161
	s_mov_b64 s[2:3], exec
	v_readlane_b32 s0, v254, 16
	v_readlane_b32 s1, v254, 17
	s_and_b64 s[0:1], s[2:3], s[0:1]
	s_mov_b64 exec, s[0:1]
	ds_write_b128 v158, v[86:89]
	s_or_b64 exec, exec, s[2:3]
	v_pk_fma_f32 v[116:117], v[60:61], v[140:141], v[80:81]
	v_pk_fma_f32 v[136:137], v[58:59], v[136:137], v[78:79]
	v_pk_fma_f32 v[116:117], v[64:65], v[134:135], v[116:117]
	v_pk_fma_f32 v[136:137], v[62:63], v[132:133], v[136:137]
	v_pk_fma_f32 v[116:117], v[72:73], v[110:111], v[116:117]
	v_lshlrev_b32_e32 v140, 16, v95
	v_and_b32_e32 v141, 0xffff0000, v95
	v_pk_fma_f32 v[146:147], v[70:71], v[106:107], v[136:137]
	v_lshlrev_b32_e32 v136, 16, v94
	v_and_b32_e32 v137, 0xffff0000, v94
	v_pk_fma_f32 v[116:117], v[68:69], v[140:141], v[116:117]
	v_pk_fma_f32 v[94:95], v[66:67], v[136:137], v[146:147]
	v_pk_mul_f32 v[146:147], v[116:117], s[36:37] op_sel_hi:[1,0]
	v_pk_mul_f32 v[160:161], v[94:95], s[36:37] op_sel_hi:[1,0]
	v_exp_f32_e32 v146, v146
	v_exp_f32_e32 v147, v147
	v_exp_f32_e32 v160, v160
	v_exp_f32_e32 v161, v161
	v_pk_fma_f32 v[114:115], v[38:39], v[114:115], v[54:55]
	v_pk_add_f32 v[146:147], v[146:147], 1.0 op_sel_hi:[1,0]
	v_pk_fma_f32 v[114:115], v[42:43], v[138:139], v[114:115]
	v_pk_add_f32 v[160:161], v[160:161], 1.0 op_sel_hi:[1,0]
	v_rcp_f32_e32 v146, v146
	v_rcp_f32_e32 v147, v147
	v_rcp_f32_e32 v160, v160
	v_rcp_f32_e32 v161, v161
	v_pk_mul_f32 v[146:147], v[116:117], v[146:147]
	v_pk_fma_f32 v[116:117], v[40:41], v[144:145], v[56:57]
	v_pk_mul_f32 v[94:95], v[94:95], v[160:161]
	v_pk_fma_f32 v[116:117], v[44:45], v[142:143], v[116:117]
	v_pk_fma_f32 v[160:161], v[50:51], v[108:109], v[114:115]
	v_lshlrev_b32_e32 v114, 16, v96
	v_and_b32_e32 v115, 0xffff0000, v96
	v_pk_fma_f32 v[144:145], v[52:53], v[112:113], v[116:117]
	v_lshlrev_b32_e32 v116, 16, v97
	v_and_b32_e32 v117, 0xffff0000, v97
	v_pk_fma_f32 v[96:97], v[46:47], v[114:115], v[160:161]
	v_pk_fma_f32 v[144:145], v[48:49], v[116:117], v[144:145]
	v_pk_mul_f32 v[162:163], v[96:97], s[36:37] op_sel_hi:[1,0]
	v_pk_mul_f32 v[160:161], v[144:145], s[36:37] op_sel_hi:[1,0]
	v_exp_f32_e32 v162, v162
	v_exp_f32_e32 v163, v163
	v_exp_f32_e32 v160, v160
	v_exp_f32_e32 v161, v161
	v_cvt_pk_bf16_f32 v94, v94, v95
	v_pk_add_f32 v[162:163], v[162:163], 1.0 op_sel_hi:[1,0]
	v_cvt_pk_bf16_f32 v95, v146, v147
	v_pk_add_f32 v[160:161], v[160:161], 1.0 op_sel_hi:[1,0]
	v_rcp_f32_e32 v162, v162
	v_rcp_f32_e32 v163, v163
	v_rcp_f32_e32 v160, v160
	v_rcp_f32_e32 v161, v161
	v_pk_mul_f32 v[96:97], v[96:97], v[162:163]
	s_nop 0
	v_cvt_pk_bf16_f32 v96, v96, v97
	v_pk_mul_f32 v[144:145], v[144:145], v[160:161]
	s_nop 0
	v_cvt_pk_bf16_f32 v97, v144, v145
	s_mov_b64 s[2:3], exec
	v_readlane_b32 s0, v254, 16
	v_readlane_b32 s1, v254, 17
	s_and_b64 s[0:1], s[2:3], s[0:1]
	s_mov_b64 exec, s[0:1]
	ds_write_b128 v158, v[94:97] offset:64
	s_or_b64 exec, exec, s[2:3]
	v_pk_fma_f32 v[132:133], v[58:59], v[132:133], v[78:79]
	v_pk_fma_f32 v[134:135], v[60:61], v[134:135], v[80:81]
	v_pk_fma_f32 v[132:133], v[62:63], v[106:107], v[132:133]
	v_pk_fma_f32 v[134:135], v[64:65], v[110:111], v[134:135]
	v_pk_fma_f32 v[146:147], v[70:71], v[136:137], v[132:133]
	v_lshlrev_b32_e32 v132, 16, v102
	v_and_b32_e32 v133, 0xffff0000, v102
	v_pk_fma_f32 v[144:145], v[72:73], v[140:141], v[134:135]
	v_lshlrev_b32_e32 v134, 16, v103
	v_and_b32_e32 v135, 0xffff0000, v103
	v_pk_fma_f32 v[102:103], v[66:67], v[132:133], v[146:147]
	v_pk_fma_f32 v[144:145], v[68:69], v[134:135], v[144:145]
	v_pk_mul_f32 v[160:161], v[102:103], s[36:37] op_sel_hi:[1,0]
	v_pk_mul_f32 v[146:147], v[144:145], s[36:37] op_sel_hi:[1,0]
	v_exp_f32_e32 v160, v160
	v_exp_f32_e32 v161, v161
	v_exp_f32_e32 v146, v146
	v_exp_f32_e32 v147, v147
	v_pk_fma_f32 v[142:143], v[40:41], v[142:143], v[56:57]
	v_pk_add_f32 v[160:161], v[160:161], 1.0 op_sel_hi:[1,0]
	v_pk_fma_f32 v[138:139], v[38:39], v[138:139], v[54:55]
	v_pk_add_f32 v[146:147], v[146:147], 1.0 op_sel_hi:[1,0]
	v_rcp_f32_e32 v160, v160
	v_rcp_f32_e32 v161, v161
	v_rcp_f32_e32 v146, v146
	v_rcp_f32_e32 v147, v147
	v_pk_fma_f32 v[142:143], v[44:45], v[112:113], v[142:143]
	v_pk_fma_f32 v[138:139], v[42:43], v[108:109], v[138:139]
	v_pk_mul_f32 v[102:103], v[102:103], v[160:161]
	v_pk_fma_f32 v[160:161], v[52:53], v[116:117], v[142:143]
	v_pk_fma_f32 v[138:139], v[50:51], v[114:115], v[138:139]
	v_lshlrev_b32_e32 v142, 16, v104
	v_and_b32_e32 v143, 0xffff0000, v104
	v_pk_mul_f32 v[144:145], v[144:145], v[146:147]
	v_lshlrev_b32_e32 v146, 16, v105
	v_and_b32_e32 v147, 0xffff0000, v105
	v_pk_fma_f32 v[104:105], v[46:47], v[142:143], v[138:139]
	v_pk_fma_f32 v[138:139], v[48:49], v[146:147], v[160:161]
	v_pk_mul_f32 v[162:163], v[104:105], s[36:37] op_sel_hi:[1,0]
	v_pk_mul_f32 v[160:161], v[138:139], s[36:37] op_sel_hi:[1,0]
	v_exp_f32_e32 v162, v162
	v_exp_f32_e32 v163, v163
	v_exp_f32_e32 v160, v160
	v_exp_f32_e32 v161, v161
	v_cvt_pk_bf16_f32 v102, v102, v103
	v_pk_add_f32 v[162:163], v[162:163], 1.0 op_sel_hi:[1,0]
	v_cvt_pk_bf16_f32 v103, v144, v145
	v_pk_add_f32 v[160:161], v[160:161], 1.0 op_sel_hi:[1,0]
	v_rcp_f32_e32 v162, v162
	v_rcp_f32_e32 v163, v163
	v_rcp_f32_e32 v160, v160
	v_rcp_f32_e32 v161, v161
	v_pk_mul_f32 v[104:105], v[104:105], v[162:163]
	s_nop 0
	v_cvt_pk_bf16_f32 v104, v104, v105
	v_pk_mul_f32 v[138:139], v[138:139], v[160:161]
	s_nop 0
	v_cvt_pk_bf16_f32 v105, v138, v139
	s_mov_b64 s[2:3], exec
	v_readlane_b32 s0, v254, 16
	v_readlane_b32 s1, v254, 17
	s_and_b64 s[0:1], s[2:3], s[0:1]
	s_mov_b64 exec, s[0:1]
	ds_write_b128 v158, v[102:105] offset:128
	s_or_b64 exec, exec, s[2:3]
	v_pk_fma_f32 v[110:111], v[60:61], v[110:111], v[80:81]
	v_pk_fma_f32 v[106:107], v[58:59], v[106:107], v[78:79]
	v_pk_fma_f32 v[110:111], v[64:65], v[140:141], v[110:111]
	v_pk_fma_f32 v[106:107], v[62:63], v[136:137], v[106:107]
	v_pk_fma_f32 v[110:111], v[72:73], v[134:135], v[110:111]
	v_pk_fma_f32 v[106:107], v[70:71], v[132:133], v[106:107]
	v_lshlrev_b32_e32 v138, 16, v98
	v_and_b32_e32 v139, 0xffff0000, v98
	v_lshlrev_b32_e32 v144, 16, v99
	v_and_b32_e32 v145, 0xffff0000, v99
	v_pk_fma_f32 v[98:99], v[66:67], v[138:139], v[106:107]
	v_pk_fma_f32 v[106:107], v[68:69], v[144:145], v[110:111]
	v_pk_mul_f32 v[160:161], v[98:99], s[36:37] op_sel_hi:[1,0]
	v_pk_mul_f32 v[110:111], v[106:107], s[36:37] op_sel_hi:[1,0]
	v_exp_f32_e32 v160, v160
	v_exp_f32_e32 v110, v110
	v_exp_f32_e32 v111, v111
	v_exp_f32_e32 v161, v161
	v_pk_fma_f32 v[108:109], v[38:39], v[108:109], v[54:55]
	v_pk_add_f32 v[110:111], v[110:111], 1.0 op_sel_hi:[1,0]
	s_nop 0
	v_rcp_f32_e32 v110, v110
	v_rcp_f32_e32 v111, v111
	v_pk_add_f32 v[160:161], v[160:161], 1.0 op_sel_hi:[1,0]
	v_pk_fma_f32 v[108:109], v[42:43], v[114:115], v[108:109]
	v_rcp_f32_e32 v160, v160
	v_rcp_f32_e32 v161, v161
	v_pk_mul_f32 v[162:163], v[106:107], v[110:111]
	v_pk_fma_f32 v[106:107], v[40:41], v[112:113], v[56:57]
	v_pk_fma_f32 v[108:109], v[50:51], v[142:143], v[108:109]
	v_pk_fma_f32 v[106:107], v[44:45], v[116:117], v[106:107]
	v_lshlrev_b32_e32 v110, 16, v101
	v_pk_fma_f32 v[112:113], v[52:53], v[146:147], v[106:107]
	v_lshlrev_b32_e32 v106, 16, v100
	v_and_b32_e32 v107, 0xffff0000, v100
	v_and_b32_e32 v111, 0xffff0000, v101
	v_pk_fma_f32 v[100:101], v[46:47], v[106:107], v[108:109]
	v_pk_mul_f32 v[98:99], v[98:99], v[160:161]
	v_pk_fma_f32 v[108:109], v[48:49], v[110:111], v[112:113]
	v_pk_mul_f32 v[160:161], v[100:101], s[36:37] op_sel_hi:[1,0]
	v_pk_mul_f32 v[112:113], v[108:109], s[36:37] op_sel_hi:[1,0]
	v_exp_f32_e32 v160, v160
	v_exp_f32_e32 v161, v161
	v_exp_f32_e32 v112, v112
	v_exp_f32_e32 v113, v113
	v_cvt_pk_bf16_f32 v98, v98, v99
	v_pk_add_f32 v[160:161], v[160:161], 1.0 op_sel_hi:[1,0]
	v_cvt_pk_bf16_f32 v99, v162, v163
	v_pk_add_f32 v[112:113], v[112:113], 1.0 op_sel_hi:[1,0]
	v_rcp_f32_e32 v160, v160
	v_rcp_f32_e32 v161, v161
	v_rcp_f32_e32 v112, v112
	v_rcp_f32_e32 v113, v113
	v_pk_mul_f32 v[100:101], v[100:101], v[160:161]
	s_nop 0
	v_cvt_pk_bf16_f32 v100, v100, v101
	v_pk_mul_f32 v[108:109], v[108:109], v[112:113]
	s_nop 0
	v_cvt_pk_bf16_f32 v101, v108, v109
	s_mov_b64 s[2:3], exec
	v_readlane_b32 s0, v254, 16
	v_readlane_b32 s1, v254, 17
	s_and_b64 s[0:1], s[2:3], s[0:1]
	s_mov_b64 exec, s[0:1]
	ds_write_b128 v158, v[98:101] offset:192
	s_or_b64 exec, exec, s[2:3]
	v_pk_fma_f32 v[108:109], v[60:61], v[140:141], v[80:81]
	v_pk_fma_f32 v[112:113], v[58:59], v[136:137], v[78:79]
	v_pk_fma_f32 v[108:109], v[64:65], v[134:135], v[108:109]
	v_pk_fma_f32 v[112:113], v[62:63], v[132:133], v[112:113]
	v_pk_fma_f32 v[136:137], v[72:73], v[144:145], v[108:109]
	v_pk_fma_f32 v[140:141], v[70:71], v[138:139], v[112:113]
	v_lshlrev_b32_e32 v108, 16, v90
	v_and_b32_e32 v109, 0xffff0000, v90
	v_lshlrev_b32_e32 v112, 16, v91
	v_and_b32_e32 v113, 0xffff0000, v91
	v_pk_fma_f32 v[90:91], v[66:67], v[108:109], v[140:141]
	v_pk_fma_f32 v[136:137], v[68:69], v[112:113], v[136:137]
	v_pk_mul_f32 v[160:161], v[90:91], s[36:37] op_sel_hi:[1,0]
	v_pk_mul_f32 v[140:141], v[136:137], s[36:37] op_sel_hi:[1,0]
	v_exp_f32_e32 v160, v160
	v_exp_f32_e32 v161, v161
	v_exp_f32_e32 v140, v140
	v_exp_f32_e32 v141, v141
	v_pk_fma_f32 v[114:115], v[38:39], v[114:115], v[54:55]
	v_pk_add_f32 v[160:161], v[160:161], 1.0 op_sel_hi:[1,0]
	v_pk_fma_f32 v[116:117], v[40:41], v[116:117], v[56:57]
	v_pk_add_f32 v[140:141], v[140:141], 1.0 op_sel_hi:[1,0]
	v_rcp_f32_e32 v160, v160
	v_rcp_f32_e32 v161, v161
	v_rcp_f32_e32 v140, v140
	v_rcp_f32_e32 v141, v141
	v_pk_fma_f32 v[114:115], v[42:43], v[142:143], v[114:115]
	v_pk_mul_f32 v[90:91], v[90:91], v[160:161]
	v_pk_fma_f32 v[116:117], v[44:45], v[146:147], v[116:117]
	v_pk_fma_f32 v[160:161], v[50:51], v[106:107], v[114:115]
	v_lshlrev_b32_e32 v114, 16, v92
	v_and_b32_e32 v115, 0xffff0000, v92
	v_pk_mul_f32 v[136:137], v[136:137], v[140:141]
	v_pk_fma_f32 v[140:141], v[52:53], v[110:111], v[116:117]
	v_lshlrev_b32_e32 v116, 16, v93
	v_and_b32_e32 v117, 0xffff0000, v93
	v_pk_fma_f32 v[92:93], v[46:47], v[114:115], v[160:161]
	v_pk_fma_f32 v[140:141], v[48:49], v[116:117], v[140:141]
	v_pk_mul_f32 v[162:163], v[92:93], s[36:37] op_sel_hi:[1,0]
	v_pk_mul_f32 v[160:161], v[140:141], s[36:37] op_sel_hi:[1,0]
	v_exp_f32_e32 v162, v162
	v_exp_f32_e32 v163, v163
	v_exp_f32_e32 v160, v160
	v_exp_f32_e32 v161, v161
	v_cvt_pk_bf16_f32 v90, v90, v91
	v_pk_add_f32 v[162:163], v[162:163], 1.0 op_sel_hi:[1,0]
	v_cvt_pk_bf16_f32 v91, v136, v137
	v_pk_add_f32 v[160:161], v[160:161], 1.0 op_sel_hi:[1,0]
	v_rcp_f32_e32 v162, v162
	v_rcp_f32_e32 v163, v163
	v_rcp_f32_e32 v160, v160
	v_rcp_f32_e32 v161, v161
	v_pk_mul_f32 v[92:93], v[92:93], v[162:163]
	s_nop 0
	v_cvt_pk_bf16_f32 v92, v92, v93
	v_pk_mul_f32 v[140:141], v[140:141], v[160:161]
	s_nop 0
	v_cvt_pk_bf16_f32 v93, v140, v141
	s_mov_b64 s[2:3], exec
	v_readlane_b32 s0, v254, 16
	v_readlane_b32 s1, v254, 17
	s_and_b64 s[0:1], s[2:3], s[0:1]
	s_mov_b64 exec, s[0:1]
	ds_write_b128 v158, v[90:93] offset:256
	s_or_b64 exec, exec, s[2:3]
	v_pk_fma_f32 v[134:135], v[60:61], v[134:135], v[80:81]
	v_pk_fma_f32 v[132:133], v[58:59], v[132:133], v[78:79]
	v_pk_fma_f32 v[134:135], v[64:65], v[144:145], v[134:135]
	v_pk_fma_f32 v[132:133], v[62:63], v[138:139], v[132:133]
	v_pk_fma_f32 v[136:137], v[72:73], v[112:113], v[134:135]
	v_lshlrev_b32_e32 v134, 16, v83
	v_and_b32_e32 v135, 0xffff0000, v83
	v_pk_fma_f32 v[140:141], v[70:71], v[108:109], v[132:133]
	v_lshlrev_b32_e32 v132, 16, v82
	v_and_b32_e32 v133, 0xffff0000, v82
	v_pk_fma_f32 v[136:137], v[68:69], v[134:135], v[136:137]
	v_pk_fma_f32 v[82:83], v[66:67], v[132:133], v[140:141]
	v_pk_mul_f32 v[140:141], v[136:137], s[36:37] op_sel_hi:[1,0]
	v_pk_mul_f32 v[160:161], v[82:83], s[36:37] op_sel_hi:[1,0]
	v_exp_f32_e32 v140, v140
	v_exp_f32_e32 v141, v141
	v_exp_f32_e32 v160, v160
	v_exp_f32_e32 v161, v161
	v_pk_add_f32 v[140:141], v[140:141], 1.0 op_sel_hi:[1,0]
	s_nop 0
	v_rcp_f32_e32 v140, v140
	v_rcp_f32_e32 v141, v141
	v_pk_add_f32 v[160:161], v[160:161], 1.0 op_sel_hi:[1,0]
	v_pk_mul_f32 v[162:163], v[136:137], v[140:141]
	v_rcp_f32_e32 v160, v160
	v_rcp_f32_e32 v161, v161
	v_pk_fma_f32 v[136:137], v[40:41], v[146:147], v[56:57]
	v_pk_fma_f32 v[140:141], v[38:39], v[142:143], v[54:55]
	v_pk_fma_f32 v[136:137], v[44:45], v[110:111], v[136:137]
	v_pk_fma_f32 v[140:141], v[42:43], v[106:107], v[140:141]
	v_pk_fma_f32 v[142:143], v[52:53], v[116:117], v[136:137]
	v_pk_fma_f32 v[146:147], v[50:51], v[114:115], v[140:141]
	v_lshlrev_b32_e32 v136, 16, v84
	v_and_b32_e32 v137, 0xffff0000, v84
	v_lshlrev_b32_e32 v140, 16, v85
	v_and_b32_e32 v141, 0xffff0000, v85
	v_pk_fma_f32 v[84:85], v[46:47], v[136:137], v[146:147]
	v_pk_mul_f32 v[82:83], v[82:83], v[160:161]
	v_pk_fma_f32 v[142:143], v[48:49], v[140:141], v[142:143]
	v_pk_mul_f32 v[160:161], v[84:85], s[36:37] op_sel_hi:[1,0]
	v_pk_mul_f32 v[146:147], v[142:143], s[36:37] op_sel_hi:[1,0]
	v_exp_f32_e32 v160, v160
	v_exp_f32_e32 v161, v161
	v_exp_f32_e32 v146, v146
	v_exp_f32_e32 v147, v147
	v_cvt_pk_bf16_f32 v82, v82, v83
	v_pk_add_f32 v[160:161], v[160:161], 1.0 op_sel_hi:[1,0]
	v_cvt_pk_bf16_f32 v83, v162, v163
	v_pk_add_f32 v[146:147], v[146:147], 1.0 op_sel_hi:[1,0]
	v_rcp_f32_e32 v160, v160
	v_rcp_f32_e32 v161, v161
	v_rcp_f32_e32 v146, v146
	v_rcp_f32_e32 v147, v147
	v_pk_mul_f32 v[84:85], v[84:85], v[160:161]
	s_nop 0
	v_cvt_pk_bf16_f32 v84, v84, v85
	v_pk_mul_f32 v[142:143], v[142:143], v[146:147]
	s_nop 0
	v_cvt_pk_bf16_f32 v85, v142, v143
	s_mov_b64 s[2:3], exec
	v_readlane_b32 s0, v254, 16
	v_readlane_b32 s1, v254, 17
	s_and_b64 s[0:1], s[2:3], s[0:1]
	s_mov_b64 exec, s[0:1]
	ds_write_b128 v158, v[82:85] offset:320
	s_or_b64 exec, exec, s[2:3]
	v_pk_fma_f32 v[138:139], v[58:59], v[138:139], v[78:79]
	v_pk_fma_f32 v[142:143], v[60:61], v[144:145], v[80:81]
	v_pk_fma_f32 v[138:139], v[62:63], v[108:109], v[138:139]
	v_pk_fma_f32 v[142:143], v[64:65], v[112:113], v[142:143]
	v_pk_fma_f32 v[146:147], v[70:71], v[132:133], v[138:139]
	v_lshlrev_b32_e32 v138, 16, v74
	v_and_b32_e32 v139, 0xffff0000, v74
	v_pk_fma_f32 v[144:145], v[72:73], v[134:135], v[142:143]
	v_lshlrev_b32_e32 v142, 16, v75
	v_and_b32_e32 v143, 0xffff0000, v75
	v_pk_fma_f32 v[74:75], v[66:67], v[138:139], v[146:147]
	v_pk_fma_f32 v[144:145], v[68:69], v[142:143], v[144:145]
	v_pk_mul_f32 v[160:161], v[74:75], s[36:37] op_sel_hi:[1,0]
	v_pk_mul_f32 v[146:147], v[144:145], s[36:37] op_sel_hi:[1,0]
	v_exp_f32_e32 v160, v160
	v_exp_f32_e32 v161, v161
	v_exp_f32_e32 v146, v146
	v_exp_f32_e32 v147, v147
	v_pk_fma_f32 v[106:107], v[38:39], v[106:107], v[54:55]
	v_pk_add_f32 v[160:161], v[160:161], 1.0 op_sel_hi:[1,0]
	v_pk_fma_f32 v[110:111], v[40:41], v[110:111], v[56:57]
	v_pk_add_f32 v[146:147], v[146:147], 1.0 op_sel_hi:[1,0]
	v_rcp_f32_e32 v160, v160
	v_rcp_f32_e32 v161, v161
	v_rcp_f32_e32 v146, v146
	v_rcp_f32_e32 v147, v147
	v_pk_fma_f32 v[106:107], v[42:43], v[114:115], v[106:107]
	v_pk_mul_f32 v[74:75], v[74:75], v[160:161]
	v_pk_fma_f32 v[110:111], v[44:45], v[116:117], v[110:111]
	v_pk_fma_f32 v[160:161], v[50:51], v[136:137], v[106:107]
	v_lshlrev_b32_e32 v106, 16, v76
	v_and_b32_e32 v107, 0xffff0000, v76
	v_pk_mul_f32 v[144:145], v[144:145], v[146:147]
	v_pk_fma_f32 v[146:147], v[52:53], v[140:141], v[110:111]
	v_lshlrev_b32_e32 v110, 16, v77
	v_and_b32_e32 v111, 0xffff0000, v77
	v_pk_fma_f32 v[76:77], v[46:47], v[106:107], v[160:161]
	v_pk_fma_f32 v[146:147], v[48:49], v[110:111], v[146:147]
	v_pk_mul_f32 v[162:163], v[76:77], s[36:37] op_sel_hi:[1,0]
	v_pk_mul_f32 v[160:161], v[146:147], s[36:37] op_sel_hi:[1,0]
	v_exp_f32_e32 v162, v162
	v_exp_f32_e32 v163, v163
	v_exp_f32_e32 v160, v160
	v_exp_f32_e32 v161, v161
	v_cvt_pk_bf16_f32 v74, v74, v75
	v_pk_add_f32 v[162:163], v[162:163], 1.0 op_sel_hi:[1,0]
	v_cvt_pk_bf16_f32 v75, v144, v145
	v_pk_add_f32 v[160:161], v[160:161], 1.0 op_sel_hi:[1,0]
	v_rcp_f32_e32 v162, v162
	v_rcp_f32_e32 v163, v163
	v_rcp_f32_e32 v160, v160
	v_rcp_f32_e32 v161, v161
	v_pk_mul_f32 v[76:77], v[76:77], v[162:163]
	s_nop 0
	v_cvt_pk_bf16_f32 v76, v76, v77
	v_pk_mul_f32 v[146:147], v[146:147], v[160:161]
	s_nop 0
	v_cvt_pk_bf16_f32 v77, v146, v147
	s_mov_b64 s[2:3], exec
	v_readlane_b32 s0, v254, 16
	v_readlane_b32 s1, v254, 17
	s_and_b64 s[0:1], s[2:3], s[0:1]
	s_mov_b64 exec, s[0:1]
	ds_write_b128 v158, v[74:77] offset:384
	s_or_b64 exec, exec, s[2:3]
	v_pk_fma_f32 v[60:61], v[60:61], v[112:113], v[80:81]
	v_pk_fma_f32 v[58:59], v[58:59], v[108:109], v[78:79]
	v_pk_fma_f32 v[40:41], v[40:41], v[116:117], v[56:57]
	v_pk_fma_f32 v[38:39], v[38:39], v[114:115], v[54:55]
	v_pk_fma_f32 v[60:61], v[64:65], v[134:135], v[60:61]
	v_pk_fma_f32 v[58:59], v[62:63], v[132:133], v[58:59]
	v_pk_fma_f32 v[40:41], v[44:45], v[140:141], v[40:41]
	v_pk_fma_f32 v[38:39], v[42:43], v[136:137], v[38:39]
	v_pk_fma_f32 v[60:61], v[72:73], v[142:143], v[60:61]
	v_pk_fma_f32 v[58:59], v[70:71], v[138:139], v[58:59]
	v_lshlrev_b32_e32 v62, 16, v34
	v_and_b32_e32 v63, 0xffff0000, v34
	v_lshlrev_b32_e32 v34, 16, v35
	v_and_b32_e32 v35, 0xffff0000, v35
	v_pk_fma_f32 v[40:41], v[52:53], v[110:111], v[40:41]
	v_pk_fma_f32 v[38:39], v[50:51], v[106:107], v[38:39]
	v_lshlrev_b32_e32 v42, 16, v36
	v_and_b32_e32 v43, 0xffff0000, v36
	v_lshlrev_b32_e32 v36, 16, v37
	v_and_b32_e32 v37, 0xffff0000, v37
	v_pk_fma_f32 v[58:59], v[66:67], v[62:63], v[58:59]
	v_pk_fma_f32 v[34:35], v[68:69], v[34:35], v[60:61]
	v_pk_fma_f32 v[38:39], v[46:47], v[42:43], v[38:39]
	v_pk_fma_f32 v[36:37], v[48:49], v[36:37], v[40:41]
	v_pk_mul_f32 v[60:61], v[34:35], s[36:37] op_sel_hi:[1,0]
	v_pk_mul_f32 v[62:63], v[58:59], s[36:37] op_sel_hi:[1,0]
	v_pk_mul_f32 v[40:41], v[36:37], s[36:37] op_sel_hi:[1,0]
	v_pk_mul_f32 v[42:43], v[38:39], s[36:37] op_sel_hi:[1,0]
	v_exp_f32_e32 v62, v62
	v_exp_f32_e32 v60, v60
	v_exp_f32_e32 v61, v61
	v_exp_f32_e32 v63, v63
	v_exp_f32_e32 v42, v42
	v_exp_f32_e32 v40, v40
	v_exp_f32_e32 v41, v41
	v_exp_f32_e32 v43, v43
	v_pk_add_f32 v[60:61], v[60:61], 1.0 op_sel_hi:[1,0]
	v_pk_add_f32 v[62:63], v[62:63], 1.0 op_sel_hi:[1,0]
	v_pk_add_f32 v[40:41], v[40:41], 1.0 op_sel_hi:[1,0]
	v_pk_add_f32 v[42:43], v[42:43], 1.0 op_sel_hi:[1,0]
	v_rcp_f32_e32 v62, v62
	v_rcp_f32_e32 v63, v63
	v_rcp_f32_e32 v44, v60
	v_rcp_f32_e32 v45, v61
	v_rcp_f32_e32 v42, v42
	v_rcp_f32_e32 v40, v40
	v_rcp_f32_e32 v41, v41
	v_rcp_f32_e32 v43, v43
	v_pk_mul_f32 v[44:45], v[34:35], v[44:45]
	v_pk_mul_f32 v[34:35], v[58:59], v[62:63]
	v_pk_mul_f32 v[40:41], v[36:37], v[40:41]
	v_pk_mul_f32 v[36:37], v[38:39], v[42:43]
	v_cvt_pk_bf16_f32 v34, v34, v35
	v_cvt_pk_bf16_f32 v35, v44, v45
	s_nop 0
	v_cvt_pk_bf16_f32 v36, v36, v37
	v_cvt_pk_bf16_f32 v37, v40, v41
	s_mov_b64 s[2:3], exec
	v_readlane_b32 s0, v254, 16
	v_readlane_b32 s1, v254, 17
	s_and_b64 s[0:1], s[2:3], s[0:1]
	s_mov_b64 exec, s[0:1]
	ds_write_b128 v158, v[34:37] offset:448
	s_or_b64 exec, exec, s[2:3]
	s_and_saveexec_b64 s[2:3], s[10:11]
	s_cbranch_execz .LBB0_1413
	v_or_b32_e32 v38, s39, v0
	v_lshlrev_b32_e32 v38, 2, v38
	global_load_dword v39, v38, s[40:41]
	global_load_dword v40, v38, s[42:43]
	s_lshl_b32 s0, s38, 6
	s_or_b32 s0, s0, s62
	s_ashr_i32 s1, s0, 31
	s_lshl_b64 s[0:1], s[0:1], 7
	s_add_u32 s0, s52, s0
	s_addc_u32 s1, s53, s1
	s_waitcnt vmcnt(0)
	v_add_f32_e32 v39, v39, v40
	v_exp_f32_e32 v39, v39
	global_store_dword v38, v39, s[0:1]
